# hg combine phase: next quad's 11 loads kept in flight while the current quad's erf-gelu is computed (double-buffered registers), grid==512 fast path
# speedup vs baseline: 1.0115x; 1.0115x over previous
; DI bf16 f2bf(float a) { return (bf16)(pack2(a, 0.f) & 0xffffu); }
; DI int opaque_tid() { int t = threadIdx.x; asm volatile("" : "+v"(t)); return t; }
; DI void peer_hg_phase(const Params& p) {
;   unsigned char* ws = p.ws;
;   const int* ex = (const int*)(ws + OFF_EX);
;   const float* gt = (const float*)(ws + OFF_GT);
;   const float* sd = (const float*)(ws + OFF_SD);
;   const float* pa = (const float*)(ws + OFF_YB);
;   u32* hgp = (u32*)(ws + OFF_HGP);
;   const int tid = opaque_tid();
;   for (size_t i = (size_t)blockIdx.x * 256 + tid; i < (size_t)T_TOK * 128; i += (size_t)gridDim.x * 256) {
;     float a = 0.f;
; #pragma unroll
;     for (int s2 = 0; s2 < 8; ++s2) a += pa[(size_t)s2 * T_TOK * 128 + i];
;     a *= sd[i];
;     const float hgv = 0.5f * a * (1.f + erff(a * 0.70710678118654752f)) * gt[i];
;     hgp[i] = ((u32)ex[i] << 16) | (u32)f2bf(hgv);
;   }
.LBB0_748:
	s_or_b64 exec, exec, s[8:9]
	v_mov_b32_e32 v2, v160
	v_readlane_b32 s0, v255, 7
	s_waitcnt lgkmcnt(0)
	s_barrier
	s_mov_b64 s[10:11], exec
	v_add_u32_e32 v32, s0, v160
	s_lshl_b32 s64, s26, 8
	s_add_u32 s68, s22, 0x10000000
	s_addc_u32 s69, s23, 0
	s_add_u32 s70, s68, 0x800000
	s_addc_u32 s71, s69, 0
	s_add_u32 s72, s70, 0x800000
	s_addc_u32 s73, s71, 0
	s_add_u32 s74, s72, 0x800000
	s_addc_u32 s75, s73, 0
	s_add_u32 s76, s74, 0x800000
	s_addc_u32 s77, s75, 0
	s_add_u32 s78, s76, 0x800000
	s_addc_u32 s79, s77, 0
	s_add_u32 s80, s78, 0x800000
	s_addc_u32 s81, s79, 0
	s_add_u32 s82, s80, 0x800000
	s_addc_u32 s83, s81, 0
	s_add_u32 s84, s22, 0x1c400000
	s_addc_u32 s85, s23, 0
	s_add_u32 s86, s22, 0x18000000
	s_addc_u32 s87, s23, 0
	s_add_u32 s88, s22, 0x17800000
	s_addc_u32 s89, s23, 0
	s_add_u32 s90, s22, 0x1b800000
	s_addc_u32 s91, s23, 0
	s_mov_b32 s92, 0x378e98ab
	s_mov_b32 s93, 0x3b7cd369
	s_mov_b32 s94, 0xbcc618b2
	s_mov_b32 s95, 0x3dda74e4
	s_mov_b32 s96, 0x3f228afd
	s_mov_b32 s97, 0x3e03c728
	s_mov_b32 s98, 0xbfb8aa3b
	s_mov_b32 s99, 0x42ce8ed0
	s_mov_b32 s100, 0xc2b17218
	s_mov_b32 s101, 0x7fffffff
	v_mov_b32_e32 v84, 0x3ba10414
	v_mov_b32_e32 v85, 0xb9c68948
	v_mov_b32_e32 v86, 0x7f800000
	s_mov_b32 s65, 0x80000
	s_cmp_lg_u32 s26, 0x200
	s_cbranch_scc1 .Lmy_hg_loop_L0
	v_lshlrev_b32_e32 v33, 4, v32
	s_lshl_b32 s66, s64, 4
	v_add_u32_e32 v35, s66, v33
	global_load_dwordx4 v[36:39], v33, s[68:69]
	global_load_dwordx4 v[40:43], v33, s[70:71]
	global_load_dwordx4 v[44:47], v33, s[72:73]
	global_load_dwordx4 v[48:51], v33, s[74:75]
	global_load_dwordx4 v[52:55], v33, s[76:77]
	global_load_dwordx4 v[56:59], v33, s[78:79]
	global_load_dwordx4 v[60:63], v33, s[80:81]
	global_load_dwordx4 v[64:67], v33, s[82:83]
	global_load_dwordx4 v[68:71], v33, s[84:85]
	global_load_dwordx4 v[72:75], v33, s[86:87]
	global_load_dwordx4 v[76:79], v33, s[88:89]
	global_load_dwordx4 v[164:167], v35, s[68:69]
	global_load_dwordx4 v[168:171], v35, s[70:71]
	global_load_dwordx4 v[172:175], v35, s[72:73]
	global_load_dwordx4 v[176:179], v35, s[74:75]
	global_load_dwordx4 v[180:183], v35, s[76:77]
	global_load_dwordx4 v[184:187], v35, s[78:79]
	global_load_dwordx4 v[188:191], v35, s[80:81]
	global_load_dwordx4 v[192:195], v35, s[82:83]
	global_load_dwordx4 v[196:199], v35, s[84:85]
	global_load_dwordx4 v[200:203], v35, s[86:87]
	global_load_dwordx4 v[204:207], v35, s[88:89]
	s_waitcnt vmcnt(21)
	v_add_f32_e32 v36, 0, v36
	v_add_f32_e32 v37, 0, v37
	v_add_f32_e32 v38, 0, v38
	v_add_f32_e32 v39, 0, v39
	s_waitcnt vmcnt(20)
	v_add_f32_e32 v36, v36, v40
	v_add_f32_e32 v37, v37, v41
	v_add_f32_e32 v38, v38, v42
	v_add_f32_e32 v39, v39, v43
	s_waitcnt vmcnt(19)
	v_add_f32_e32 v36, v36, v44
	v_add_f32_e32 v37, v37, v45
	v_add_f32_e32 v38, v38, v46
	v_add_f32_e32 v39, v39, v47
	s_waitcnt vmcnt(18)
	v_add_f32_e32 v36, v36, v48
	v_add_f32_e32 v37, v37, v49
	v_add_f32_e32 v38, v38, v50
	v_add_f32_e32 v39, v39, v51
	s_waitcnt vmcnt(17)
	v_add_f32_e32 v36, v36, v52
	v_add_f32_e32 v37, v37, v53
	v_add_f32_e32 v38, v38, v54
	v_add_f32_e32 v39, v39, v55
	s_waitcnt vmcnt(16)
	v_add_f32_e32 v36, v36, v56
	v_add_f32_e32 v37, v37, v57
	v_add_f32_e32 v38, v38, v58
	v_add_f32_e32 v39, v39, v59
	s_waitcnt vmcnt(15)
	v_add_f32_e32 v36, v36, v60
	v_add_f32_e32 v37, v37, v61
	v_add_f32_e32 v38, v38, v62
	v_add_f32_e32 v39, v39, v63
	s_waitcnt vmcnt(14)
	v_add_f32_e32 v36, v36, v64
	v_add_f32_e32 v37, v37, v65
	v_add_f32_e32 v38, v38, v66
	v_add_f32_e32 v39, v39, v67
	s_waitcnt vmcnt(13)
	v_mul_f32_e32 v36, v36, v68
	v_mul_f32_e32 v37, v37, v69
	v_mul_f32_e32 v38, v38, v70
	v_mul_f32_e32 v39, v39, v71
	v_mul_f32_e32 v40, 0x3f3504f3, v36
	v_cmp_nlt_f32_e64 s[42:43], |v40|, 1.0
	s_and_saveexec_b64 s[44:45], s[42:43]
	s_xor_b64 s[42:43], exec, s[44:45]
	s_cbranch_execz .Lmy_hg_b_L0_0_u0
	v_fma_f32 v41, |v40|, s92, v85
	v_fma_f32 v41, |v40|, v41, s93
	v_fma_f32 v41, |v40|, v41, s94
	v_fma_f32 v41, |v40|, v41, s95
	v_fma_f32 v41, |v40|, v41, s96
	v_fma_f32 v41, |v40|, v41, s97
	v_fma_f32 v41, |v40|, v41, |v40|
	v_mul_f32_e32 v42, 0xbfb8aa3b, v41
	v_fma_f32 v43, v41, s98, -v42
	v_rndne_f32_e32 v44, v42
	v_fmac_f32_e32 v43, 0xb2a5705f, v41
	v_sub_f32_e32 v42, v42, v44
	v_add_f32_e32 v42, v42, v43
	v_cvt_i32_f32_e32 v43, v44
	v_exp_f32_e32 v42, v42
	v_cmp_nlt_f32_e32 vcc, s99, v41
	v_ldexp_f32 v42, v42, v43
	s_nop 0
	v_cndmask_b32_e32 v42, 0, v42, vcc
	v_cmp_ngt_f32_e32 vcc, s100, v41
	s_nop 1
	v_cndmask_b32_e32 v41, v86, v42, vcc
	v_sub_f32_e32 v41, 1.0, v41

; DI bf16 f2bf(float a) { return (bf16)(pack2(a, 0.f) & 0xffffu); }
; DI void peer_hg_phase(const Params& p) {
;     ...
;     const float hgv = 0.5f * a * (1.f + erff(a * 0.70710678118654752f)) * gt[i];
;     hgp[i] = ((u32)ex[i] << 16) | (u32)f2bf(hgv);
.Lmy_hg_j_L0_0_u0:
	s_or_b64 exec, exec, s[42:43]
	v_bfi_b32 v40, s101, v41, v40
	v_mul_f32_e32 v36, 0.5, v36
	v_add_f32_e32 v40, 1.0, v40
	v_mul_f32_e32 v36, v36, v40
	s_waitcnt vmcnt(12)
	v_mul_f32_e32 v36, v72, v36
	v_cvt_pk_bf16_f32 v36, v36, v36
	v_and_b32_e32 v36, 0xffff, v36
	s_waitcnt vmcnt(11)
	v_lshl_or_b32 v80, v76, 16, v36
	v_mul_f32_e32 v40, 0x3f3504f3, v37
	v_cmp_nlt_f32_e64 s[42:43], |v40|, 1.0
	s_and_saveexec_b64 s[44:45], s[42:43]
	s_xor_b64 s[42:43], exec, s[44:45]
	s_cbranch_execz .Lmy_hg_b_L0_1_u0
	v_fma_f32 v41, |v40|, s92, v85
	v_fma_f32 v41, |v40|, v41, s93
	v_fma_f32 v41, |v40|, v41, s94
	v_fma_f32 v41, |v40|, v41, s95
	v_fma_f32 v41, |v40|, v41, s96
	v_fma_f32 v41, |v40|, v41, s97
	v_fma_f32 v41, |v40|, v41, |v40|
	v_mul_f32_e32 v42, 0xbfb8aa3b, v41
	v_fma_f32 v43, v41, s98, -v42
	v_rndne_f32_e32 v44, v42
	v_fmac_f32_e32 v43, 0xb2a5705f, v41
	v_sub_f32_e32 v42, v42, v44
	v_add_f32_e32 v42, v42, v43
	v_cvt_i32_f32_e32 v43, v44
	v_exp_f32_e32 v42, v42
	v_cmp_nlt_f32_e32 vcc, s99, v41
	v_ldexp_f32 v42, v42, v43
	s_nop 0
	v_cndmask_b32_e32 v42, 0, v42, vcc
	v_cmp_ngt_f32_e32 vcc, s100, v41
	s_nop 1
	v_cndmask_b32_e32 v41, v86, v42, vcc
	v_sub_f32_e32 v41, 1.0, v41

; DI bf16 f2bf(float a) { return (bf16)(pack2(a, 0.f) & 0xffffu); }
; DI void peer_hg_phase(const Params& p) {
;     ...
;   for (size_t i = (size_t)blockIdx.x * 256 + tid; i < (size_t)T_TOK * 128; i += (size_t)gridDim.x * 256) {
;     float a = 0.f;
; #pragma unroll
;     for (int s2 = 0; s2 < 8; ++s2) a += pa[(size_t)s2 * T_TOK * 128 + i];
;     a *= sd[i];
;     const float hgv = 0.5f * a * (1.f + erff(a * 0.70710678118654752f)) * gt[i];
;     hgp[i] = ((u32)ex[i] << 16) | (u32)f2bf(hgv);
;   }
.Lmy_hg_j_L0_3_u0:
	s_or_b64 exec, exec, s[42:43]
	v_bfi_b32 v40, s101, v41, v40
	v_mul_f32_e32 v39, 0.5, v39
	v_add_f32_e32 v40, 1.0, v40
	v_mul_f32_e32 v39, v39, v40
	v_mul_f32_e32 v39, v75, v39
	v_cvt_pk_bf16_f32 v39, v39, v39
	v_and_b32_e32 v39, 0xffff, v39
	v_lshl_or_b32 v83, v79, 16, v39
	global_store_dwordx4 v33, v[80:83], s[90:91]
	v_add_u32_e32 v33, s66, v35
	global_load_dwordx4 v[36:39], v33, s[68:69]
	global_load_dwordx4 v[40:43], v33, s[70:71]
	global_load_dwordx4 v[44:47], v33, s[72:73]
	global_load_dwordx4 v[48:51], v33, s[74:75]
	global_load_dwordx4 v[52:55], v33, s[76:77]
	global_load_dwordx4 v[56:59], v33, s[78:79]
	global_load_dwordx4 v[60:63], v33, s[80:81]
	global_load_dwordx4 v[64:67], v33, s[82:83]
	global_load_dwordx4 v[68:71], v33, s[84:85]
	global_load_dwordx4 v[72:75], v33, s[86:87]
	global_load_dwordx4 v[76:79], v33, s[88:89]
	s_waitcnt vmcnt(21)
	v_add_f32_e32 v164, 0, v164
	v_add_f32_e32 v165, 0, v165
	v_add_f32_e32 v166, 0, v166
	v_add_f32_e32 v167, 0, v167
	s_waitcnt vmcnt(20)
	v_add_f32_e32 v164, v164, v168
	v_add_f32_e32 v165, v165, v169
	v_add_f32_e32 v166, v166, v170
	v_add_f32_e32 v167, v167, v171
	s_waitcnt vmcnt(19)
	v_add_f32_e32 v164, v164, v172
	v_add_f32_e32 v165, v165, v173
	v_add_f32_e32 v166, v166, v174
	v_add_f32_e32 v167, v167, v175
	s_waitcnt vmcnt(18)
	v_add_f32_e32 v164, v164, v176
	v_add_f32_e32 v165, v165, v177
	v_add_f32_e32 v166, v166, v178
	v_add_f32_e32 v167, v167, v179
	s_waitcnt vmcnt(17)
	v_add_f32_e32 v164, v164, v180
	v_add_f32_e32 v165, v165, v181
	v_add_f32_e32 v166, v166, v182
	v_add_f32_e32 v167, v167, v183
	s_waitcnt vmcnt(16)
	v_add_f32_e32 v164, v164, v184
	v_add_f32_e32 v165, v165, v185
	v_add_f32_e32 v166, v166, v186
	v_add_f32_e32 v167, v167, v187
	s_waitcnt vmcnt(15)
	v_add_f32_e32 v164, v164, v188
	v_add_f32_e32 v165, v165, v189
	v_add_f32_e32 v166, v166, v190
	v_add_f32_e32 v167, v167, v191
	s_waitcnt vmcnt(14)
	v_add_f32_e32 v164, v164, v192
	v_add_f32_e32 v165, v165, v193
	v_add_f32_e32 v166, v166, v194
	v_add_f32_e32 v167, v167, v195
	s_waitcnt vmcnt(13)
	v_mul_f32_e32 v164, v164, v196
	v_mul_f32_e32 v165, v165, v197
	v_mul_f32_e32 v166, v166, v198
	v_mul_f32_e32 v167, v167, v199
	v_mul_f32_e32 v168, 0x3f3504f3, v164
	v_cmp_nlt_f32_e64 s[42:43], |v168|, 1.0
	s_and_saveexec_b64 s[44:45], s[42:43]
	s_xor_b64 s[42:43], exec, s[44:45]
	s_cbranch_execz .Lmy_hg_b_L0_0_u1
	v_fma_f32 v169, |v168|, s92, v85
	v_fma_f32 v169, |v168|, v169, s93
	v_fma_f32 v169, |v168|, v169, s94
	v_fma_f32 v169, |v168|, v169, s95
	v_fma_f32 v169, |v168|, v169, s96
	v_fma_f32 v169, |v168|, v169, s97
	v_fma_f32 v169, |v168|, v169, |v168|
	v_mul_f32_e32 v170, 0xbfb8aa3b, v169
	v_fma_f32 v171, v169, s98, -v170
	v_rndne_f32_e32 v172, v170
	v_fmac_f32_e32 v171, 0xb2a5705f, v169
	v_sub_f32_e32 v170, v170, v172
	v_add_f32_e32 v170, v170, v171
	v_cvt_i32_f32_e32 v171, v172
	v_exp_f32_e32 v170, v170
	v_cmp_nlt_f32_e32 vcc, s99, v169
	v_ldexp_f32 v170, v170, v171
	s_nop 0
	v_cndmask_b32_e32 v170, 0, v170, vcc
	v_cmp_ngt_f32_e32 vcc, s100, v169
	s_nop 1
	v_cndmask_b32_e32 v169, v86, v170, vcc
	v_sub_f32_e32 v169, 1.0, v169
.Lmy_hg_b_L0_0_u1:
	s_andn2_saveexec_b64 s[42:43], s[42:43]
	s_cbranch_execz .Lmy_hg_j_L0_0_u1
	v_mul_f32_e32 v169, v168, v168
	v_fmamk_f32 v170, v169, 0xba1345e1, v84
	v_fmaak_f32 v170, v169, v170, 0xbcdac9b8
	v_fmaak_f32 v170, v169, v170, 0x3de703be
	v_fmaak_f32 v170, v169, v170, 0xbec09330
	v_fmaak_f32 v169, v169, v170, 0x3e0375d0
	v_fma_f32 v169, |v168|, v169, |v168|
.Lmy_hg_j_L0_0_u1:
	s_or_b64 exec, exec, s[42:43]
	v_bfi_b32 v168, s101, v169, v168
	v_mul_f32_e32 v164, 0.5, v164
	v_add_f32_e32 v168, 1.0, v168
	v_mul_f32_e32 v164, v164, v168
	s_waitcnt vmcnt(12)
	v_mul_f32_e32 v164, v200, v164
	v_cvt_pk_bf16_f32 v164, v164, v164
	v_and_b32_e32 v164, 0xffff, v164
	s_waitcnt vmcnt(11)
	v_lshl_or_b32 v208, v204, 16, v164
	v_mul_f32_e32 v168, 0x3f3504f3, v165
	v_cmp_nlt_f32_e64 s[42:43], |v168|, 1.0
	s_and_saveexec_b64 s[44:45], s[42:43]
	s_xor_b64 s[42:43], exec, s[44:45]
	s_cbranch_execz .Lmy_hg_b_L0_1_u1
	v_fma_f32 v169, |v168|, s92, v85
	v_fma_f32 v169, |v168|, v169, s93
	v_fma_f32 v169, |v168|, v169, s94
	v_fma_f32 v169, |v168|, v169, s95
	v_fma_f32 v169, |v168|, v169, s96
	v_fma_f32 v169, |v168|, v169, s97
	v_fma_f32 v169, |v168|, v169, |v168|
	v_mul_f32_e32 v170, 0xbfb8aa3b, v169
	v_fma_f32 v171, v169, s98, -v170
	v_rndne_f32_e32 v172, v170
	v_fmac_f32_e32 v171, 0xb2a5705f, v169
	v_sub_f32_e32 v170, v170, v172
	v_add_f32_e32 v170, v170, v171
	v_cvt_i32_f32_e32 v171, v172
	v_exp_f32_e32 v170, v170
	v_cmp_nlt_f32_e32 vcc, s99, v169
	v_ldexp_f32 v170, v170, v171
	s_nop 0
	v_cndmask_b32_e32 v170, 0, v170, vcc
	v_cmp_ngt_f32_e32 vcc, s100, v169
	s_nop 1
	v_cndmask_b32_e32 v169, v86, v170, vcc
	v_sub_f32_e32 v169, 1.0, v169

; DI bf16 f2bf(float a) { return (bf16)(pack2(a, 0.f) & 0xffffu); }
; DI void peer_hg_phase(const Params& p) {
;     ...
;     const float hgv = 0.5f * a * (1.f + erff(a * 0.70710678118654752f)) * gt[i];
;     hgp[i] = ((u32)ex[i] << 16) | (u32)f2bf(hgv);
.Lmy_hg_j_L0_1_u1:
	s_or_b64 exec, exec, s[42:43]
	v_bfi_b32 v168, s101, v169, v168
	v_mul_f32_e32 v165, 0.5, v165
	v_add_f32_e32 v168, 1.0, v168
	v_mul_f32_e32 v165, v165, v168
	v_mul_f32_e32 v165, v201, v165
	v_cvt_pk_bf16_f32 v165, v165, v165
	v_and_b32_e32 v165, 0xffff, v165
	v_lshl_or_b32 v209, v205, 16, v165
	v_mul_f32_e32 v168, 0x3f3504f3, v166
	v_cmp_nlt_f32_e64 s[42:43], |v168|, 1.0
	s_and_saveexec_b64 s[44:45], s[42:43]
	s_xor_b64 s[42:43], exec, s[44:45]
	s_cbranch_execz .Lmy_hg_b_L0_2_u1
	v_fma_f32 v169, |v168|, s92, v85
	v_fma_f32 v169, |v168|, v169, s93
	v_fma_f32 v169, |v168|, v169, s94
	v_fma_f32 v169, |v168|, v169, s95
	v_fma_f32 v169, |v168|, v169, s96
	v_fma_f32 v169, |v168|, v169, s97
	v_fma_f32 v169, |v168|, v169, |v168|
	v_mul_f32_e32 v170, 0xbfb8aa3b, v169
	v_fma_f32 v171, v169, s98, -v170
	v_rndne_f32_e32 v172, v170
	v_fmac_f32_e32 v171, 0xb2a5705f, v169
	v_sub_f32_e32 v170, v170, v172
	v_add_f32_e32 v170, v170, v171
	v_cvt_i32_f32_e32 v171, v172
	v_exp_f32_e32 v170, v170
	v_cmp_nlt_f32_e32 vcc, s99, v169
	v_ldexp_f32 v170, v170, v171
	s_nop 0
	v_cndmask_b32_e32 v170, 0, v170, vcc
	v_cmp_ngt_f32_e32 vcc, s100, v169
	s_nop 1
	v_cndmask_b32_e32 v169, v86, v170, vcc
	v_sub_f32_e32 v169, 1.0, v169

; DI bf16 f2bf(float a) { return (bf16)(pack2(a, 0.f) & 0xffffu); }
; DI void peer_hg_phase(const Params& p) {
;     ...
;     const float hgv = 0.5f * a * (1.f + erff(a * 0.70710678118654752f)) * gt[i];
;     hgp[i] = ((u32)ex[i] << 16) | (u32)f2bf(hgv);
.Lmy_hg_j_L0_2_u1:
	s_or_b64 exec, exec, s[42:43]
	v_bfi_b32 v168, s101, v169, v168
	v_mul_f32_e32 v166, 0.5, v166
	v_add_f32_e32 v168, 1.0, v168
	v_mul_f32_e32 v166, v166, v168
	v_mul_f32_e32 v166, v202, v166
	v_cvt_pk_bf16_f32 v166, v166, v166
	v_and_b32_e32 v166, 0xffff, v166
	v_lshl_or_b32 v210, v206, 16, v166
	v_mul_f32_e32 v168, 0x3f3504f3, v167
	v_cmp_nlt_f32_e64 s[42:43], |v168|, 1.0
	s_and_saveexec_b64 s[44:45], s[42:43]
	s_xor_b64 s[42:43], exec, s[44:45]
	s_cbranch_execz .Lmy_hg_b_L0_3_u1
	v_fma_f32 v169, |v168|, s92, v85
	v_fma_f32 v169, |v168|, v169, s93
	v_fma_f32 v169, |v168|, v169, s94
	v_fma_f32 v169, |v168|, v169, s95
	v_fma_f32 v169, |v168|, v169, s96
	v_fma_f32 v169, |v168|, v169, s97
	v_fma_f32 v169, |v168|, v169, |v168|
	v_mul_f32_e32 v170, 0xbfb8aa3b, v169
	v_fma_f32 v171, v169, s98, -v170
	v_rndne_f32_e32 v172, v170
	v_fmac_f32_e32 v171, 0xb2a5705f, v169
	v_sub_f32_e32 v170, v170, v172
	v_add_f32_e32 v170, v170, v171
	v_cvt_i32_f32_e32 v171, v172
	v_exp_f32_e32 v170, v170
	v_cmp_nlt_f32_e32 vcc, s99, v169
	v_ldexp_f32 v170, v170, v171
	s_nop 0
	v_cndmask_b32_e32 v170, 0, v170, vcc
	v_cmp_ngt_f32_e32 vcc, s100, v169
	s_nop 1
	v_cndmask_b32_e32 v169, v86, v170, vcc
	v_sub_f32_e32 v169, 1.0, v169

; DI bf16 f2bf(float a) { return (bf16)(pack2(a, 0.f) & 0xffffu); }
; DI void peer_hg_phase(const Params& p) {
;     ...
;   for (size_t i = (size_t)blockIdx.x * 256 + tid; i < (size_t)T_TOK * 128; i += (size_t)gridDim.x * 256) {
;     float a = 0.f;
; #pragma unroll
;     for (int s2 = 0; s2 < 8; ++s2) a += pa[(size_t)s2 * T_TOK * 128 + i];
;     a *= sd[i];
;     const float hgv = 0.5f * a * (1.f + erff(a * 0.70710678118654752f)) * gt[i];
;     hgp[i] = ((u32)ex[i] << 16) | (u32)f2bf(hgv);
;   }
.Lmy_hg_j_L0_3_u1:
	s_or_b64 exec, exec, s[42:43]
	v_bfi_b32 v168, s101, v169, v168
	v_mul_f32_e32 v167, 0.5, v167
	v_add_f32_e32 v168, 1.0, v168
	v_mul_f32_e32 v167, v167, v168
	v_mul_f32_e32 v167, v203, v167
	v_cvt_pk_bf16_f32 v167, v167, v167
	v_and_b32_e32 v167, 0xffff, v167
	v_lshl_or_b32 v211, v207, 16, v167
	global_store_dwordx4 v35, v[208:211], s[90:91]
	v_add_u32_e32 v35, s66, v33
	global_load_dwordx4 v[164:167], v35, s[68:69]
	global_load_dwordx4 v[168:171], v35, s[70:71]
	global_load_dwordx4 v[172:175], v35, s[72:73]
	global_load_dwordx4 v[176:179], v35, s[74:75]
	global_load_dwordx4 v[180:183], v35, s[76:77]
	global_load_dwordx4 v[184:187], v35, s[78:79]
	global_load_dwordx4 v[188:191], v35, s[80:81]
	global_load_dwordx4 v[192:195], v35, s[82:83]
	global_load_dwordx4 v[196:199], v35, s[84:85]
	global_load_dwordx4 v[200:203], v35, s[86:87]
	global_load_dwordx4 v[204:207], v35, s[88:89]
	s_waitcnt vmcnt(21)
	v_add_f32_e32 v36, 0, v36
	v_add_f32_e32 v37, 0, v37
	v_add_f32_e32 v38, 0, v38
	v_add_f32_e32 v39, 0, v39
	s_waitcnt vmcnt(20)
	v_add_f32_e32 v36, v36, v40
	v_add_f32_e32 v37, v37, v41
	v_add_f32_e32 v38, v38, v42
	v_add_f32_e32 v39, v39, v43
	s_waitcnt vmcnt(19)
	v_add_f32_e32 v36, v36, v44
	v_add_f32_e32 v37, v37, v45
	v_add_f32_e32 v38, v38, v46
	v_add_f32_e32 v39, v39, v47
	s_waitcnt vmcnt(18)
	v_add_f32_e32 v36, v36, v48
	v_add_f32_e32 v37, v37, v49
	v_add_f32_e32 v38, v38, v50
	v_add_f32_e32 v39, v39, v51
	s_waitcnt vmcnt(17)
	v_add_f32_e32 v36, v36, v52
	v_add_f32_e32 v37, v37, v53
	v_add_f32_e32 v38, v38, v54
	v_add_f32_e32 v39, v39, v55
	s_waitcnt vmcnt(16)
	v_add_f32_e32 v36, v36, v56
	v_add_f32_e32 v37, v37, v57
	v_add_f32_e32 v38, v38, v58
	v_add_f32_e32 v39, v39, v59
	s_waitcnt vmcnt(15)
	v_add_f32_e32 v36, v36, v60
	v_add_f32_e32 v37, v37, v61
	v_add_f32_e32 v38, v38, v62
	v_add_f32_e32 v39, v39, v63
	s_waitcnt vmcnt(14)
	v_add_f32_e32 v36, v36, v64
	v_add_f32_e32 v37, v37, v65
	v_add_f32_e32 v38, v38, v66
	v_add_f32_e32 v39, v39, v67
	s_waitcnt vmcnt(13)
	v_mul_f32_e32 v36, v36, v68
	v_mul_f32_e32 v37, v37, v69
	v_mul_f32_e32 v38, v38, v70
	v_mul_f32_e32 v39, v39, v71
	v_mul_f32_e32 v40, 0x3f3504f3, v36
	v_cmp_nlt_f32_e64 s[42:43], |v40|, 1.0
	s_and_saveexec_b64 s[44:45], s[42:43]
	s_xor_b64 s[42:43], exec, s[44:45]
	s_cbranch_execz .Lmy_hg_b_L0_0_u2
	v_fma_f32 v41, |v40|, s92, v85
	v_fma_f32 v41, |v40|, v41, s93
	v_fma_f32 v41, |v40|, v41, s94
	v_fma_f32 v41, |v40|, v41, s95
	v_fma_f32 v41, |v40|, v41, s96
	v_fma_f32 v41, |v40|, v41, s97
	v_fma_f32 v41, |v40|, v41, |v40|
	v_mul_f32_e32 v42, 0xbfb8aa3b, v41
	v_fma_f32 v43, v41, s98, -v42
	v_rndne_f32_e32 v44, v42
	v_fmac_f32_e32 v43, 0xb2a5705f, v41
	v_sub_f32_e32 v42, v42, v44
	v_add_f32_e32 v42, v42, v43
	v_cvt_i32_f32_e32 v43, v44
	v_exp_f32_e32 v42, v42
	v_cmp_nlt_f32_e32 vcc, s99, v41
	v_ldexp_f32 v42, v42, v43
	s_nop 0
	v_cndmask_b32_e32 v42, 0, v42, vcc
	v_cmp_ngt_f32_e32 vcc, s100, v41
	s_nop 1
	v_cndmask_b32_e32 v41, v86, v42, vcc
	v_sub_f32_e32 v41, 1.0, v41

; DI bf16 f2bf(float a) { return (bf16)(pack2(a, 0.f) & 0xffffu); }
; DI void peer_hg_phase(const Params& p) {
;     ...
;   for (size_t i = (size_t)blockIdx.x * 256 + tid; i < (size_t)T_TOK * 128; i += (size_t)gridDim.x * 256) {
;     float a = 0.f;
; #pragma unroll
;     for (int s2 = 0; s2 < 8; ++s2) a += pa[(size_t)s2 * T_TOK * 128 + i];
;     a *= sd[i];
;     const float hgv = 0.5f * a * (1.f + erff(a * 0.70710678118654752f)) * gt[i];
;     hgp[i] = ((u32)ex[i] << 16) | (u32)f2bf(hgv);
;   }
.Lmy_hg_j_L0_3_u2:
	s_or_b64 exec, exec, s[42:43]
	v_bfi_b32 v40, s101, v41, v40
	v_mul_f32_e32 v39, 0.5, v39
	v_add_f32_e32 v40, 1.0, v40
	v_mul_f32_e32 v39, v39, v40
	v_mul_f32_e32 v39, v75, v39
	v_cvt_pk_bf16_f32 v39, v39, v39
	v_and_b32_e32 v39, 0xffff, v39
	v_lshl_or_b32 v83, v79, 16, v39
	global_store_dwordx4 v33, v[80:83], s[90:91]
	s_waitcnt vmcnt(10)
	v_add_f32_e32 v164, 0, v164
	v_add_f32_e32 v165, 0, v165
	v_add_f32_e32 v166, 0, v166
	v_add_f32_e32 v167, 0, v167
	s_waitcnt vmcnt(9)
	v_add_f32_e32 v164, v164, v168
	v_add_f32_e32 v165, v165, v169
	v_add_f32_e32 v166, v166, v170
	v_add_f32_e32 v167, v167, v171
	s_waitcnt vmcnt(8)
	v_add_f32_e32 v164, v164, v172
	v_add_f32_e32 v165, v165, v173
	v_add_f32_e32 v166, v166, v174
	v_add_f32_e32 v167, v167, v175
	s_waitcnt vmcnt(7)
	v_add_f32_e32 v164, v164, v176
	v_add_f32_e32 v165, v165, v177
	v_add_f32_e32 v166, v166, v178
	v_add_f32_e32 v167, v167, v179
	s_waitcnt vmcnt(6)
	v_add_f32_e32 v164, v164, v180
	v_add_f32_e32 v165, v165, v181
	v_add_f32_e32 v166, v166, v182
	v_add_f32_e32 v167, v167, v183
	s_waitcnt vmcnt(5)
	v_add_f32_e32 v164, v164, v184
	v_add_f32_e32 v165, v165, v185
	v_add_f32_e32 v166, v166, v186
	v_add_f32_e32 v167, v167, v187
	s_waitcnt vmcnt(4)
	v_add_f32_e32 v164, v164, v188
	v_add_f32_e32 v165, v165, v189
	v_add_f32_e32 v166, v166, v190
	v_add_f32_e32 v167, v167, v191
	s_waitcnt vmcnt(3)
	v_add_f32_e32 v164, v164, v192
	v_add_f32_e32 v165, v165, v193
	v_add_f32_e32 v166, v166, v194
	v_add_f32_e32 v167, v167, v195
	s_waitcnt vmcnt(2)
	v_mul_f32_e32 v164, v164, v196
	v_mul_f32_e32 v165, v165, v197
	v_mul_f32_e32 v166, v166, v198
	v_mul_f32_e32 v167, v167, v199
	v_mul_f32_e32 v168, 0x3f3504f3, v164
	v_cmp_nlt_f32_e64 s[42:43], |v168|, 1.0
	s_and_saveexec_b64 s[44:45], s[42:43]
	s_xor_b64 s[42:43], exec, s[44:45]
	s_cbranch_execz .Lmy_hg_b_L0_0_u3
	v_fma_f32 v169, |v168|, s92, v85
	v_fma_f32 v169, |v168|, v169, s93
	v_fma_f32 v169, |v168|, v169, s94
	v_fma_f32 v169, |v168|, v169, s95
	v_fma_f32 v169, |v168|, v169, s96
	v_fma_f32 v169, |v168|, v169, s97
	v_fma_f32 v169, |v168|, v169, |v168|
	v_mul_f32_e32 v170, 0xbfb8aa3b, v169
	v_fma_f32 v171, v169, s98, -v170
	v_rndne_f32_e32 v172, v170
	v_fmac_f32_e32 v171, 0xb2a5705f, v169
	v_sub_f32_e32 v170, v170, v172
	v_add_f32_e32 v170, v170, v171
	v_cvt_i32_f32_e32 v171, v172
	v_exp_f32_e32 v170, v170
	v_cmp_nlt_f32_e32 vcc, s99, v169
	v_ldexp_f32 v170, v170, v171
	s_nop 0
	v_cndmask_b32_e32 v170, 0, v170, vcc
	v_cmp_ngt_f32_e32 vcc, s100, v169
	s_nop 1
	v_cndmask_b32_e32 v169, v86, v170, vcc
	v_sub_f32_e32 v169, 1.0, v169

; DI bf16 f2bf(float a) { return (bf16)(pack2(a, 0.f) & 0xffffu); }
; DI void peer_hg_phase(const Params& p) {
;     ...
;     const float hgv = 0.5f * a * (1.f + erff(a * 0.70710678118654752f)) * gt[i];
;     hgp[i] = ((u32)ex[i] << 16) | (u32)f2bf(hgv);
.Lmy_hg_j_L0_0_u3:
	s_or_b64 exec, exec, s[42:43]
	v_bfi_b32 v168, s101, v169, v168
	v_mul_f32_e32 v164, 0.5, v164
	v_add_f32_e32 v168, 1.0, v168
	v_mul_f32_e32 v164, v164, v168
	s_waitcnt vmcnt(1)
	v_mul_f32_e32 v164, v200, v164
	v_cvt_pk_bf16_f32 v164, v164, v164
	v_and_b32_e32 v164, 0xffff, v164
	s_waitcnt vmcnt(0)
	v_lshl_or_b32 v208, v204, 16, v164
	v_mul_f32_e32 v168, 0x3f3504f3, v165
	v_cmp_nlt_f32_e64 s[42:43], |v168|, 1.0
	s_and_saveexec_b64 s[44:45], s[42:43]
	s_xor_b64 s[42:43], exec, s[44:45]
	s_cbranch_execz .Lmy_hg_b_L0_1_u3
	v_fma_f32 v169, |v168|, s92, v85
	v_fma_f32 v169, |v168|, v169, s93
	v_fma_f32 v169, |v168|, v169, s94
	v_fma_f32 v169, |v168|, v169, s95
	v_fma_f32 v169, |v168|, v169, s96
	v_fma_f32 v169, |v168|, v169, s97
	v_fma_f32 v169, |v168|, v169, |v168|
	v_mul_f32_e32 v170, 0xbfb8aa3b, v169
	v_fma_f32 v171, v169, s98, -v170
	v_rndne_f32_e32 v172, v170
	v_fmac_f32_e32 v171, 0xb2a5705f, v169
	v_sub_f32_e32 v170, v170, v172
	v_add_f32_e32 v170, v170, v171
	v_cvt_i32_f32_e32 v171, v172
	v_exp_f32_e32 v170, v170
	v_cmp_nlt_f32_e32 vcc, s99, v169
	v_ldexp_f32 v170, v170, v171
	s_nop 0
	v_cndmask_b32_e32 v170, 0, v170, vcc
	v_cmp_ngt_f32_e32 vcc, s100, v169
	s_nop 1
	v_cndmask_b32_e32 v169, v86, v170, vcc
	v_sub_f32_e32 v169, 1.0, v169

; DI bf16 f2bf(float a) { return (bf16)(pack2(a, 0.f) & 0xffffu); }
; DI void peer_hg_phase(const Params& p) {
;     ...
;     const float hgv = 0.5f * a * (1.f + erff(a * 0.70710678118654752f)) * gt[i];
;     hgp[i] = ((u32)ex[i] << 16) | (u32)f2bf(hgv);
.Lmy_hg_j_L0_3_u3:
	s_or_b64 exec, exec, s[42:43]
	v_bfi_b32 v168, s101, v169, v168
	v_mul_f32_e32 v167, 0.5, v167
	v_add_f32_e32 v168, 1.0, v168
	v_mul_f32_e32 v167, v167, v168
	v_mul_f32_e32 v167, v203, v167
	v_cvt_pk_bf16_f32 v167, v167, v167
	v_and_b32_e32 v167, 0xffff, v167
	v_lshl_or_b32 v211, v207, 16, v167
	global_store_dwordx4 v35, v[208:211], s[90:91]
	s_branch .Lmy_hg_done2_L0

; DI unsigned xb_ld(unsigned* p)              { return __hip_atomic_load(p, __ATOMIC_RELAXED, __HIP_MEMORY_SCOPE_AGENT); }
; DI void xcd_barrier_complete(unsigned* bar, unsigned x, unsigned& nloc, unsigned& nx) {
;   const unsigned G = gridDim.x * gridDim.y * gridDim.z;
;   unsigned sum, cnt, mine, sp = 0u;
;   for (;;) {
;     sum = 0u; cnt = 0u; mine = 0u;
; #pragma unroll
;     for (unsigned j = 0; j < 16; ++j) { const unsigned c = xb_ld(&bar[XB_XCNT(j)]); sum += c; cnt += (c > 0u) ? 1u : 0u; mine = (j == x) ? c : mine; }
; DI void xcd_barrier(const XcdBarrier& b) {
;   asm volatile("s_waitcnt vmcnt(0)" ::: "memory");
;   __syncthreads();
;   if (threadIdx.x == 0) {
;     unsigned* bar = b.bar;
;     __builtin_amdgcn_s_waitcnt(0);
;     unsigned nloc = b.st[0], nx = b.st[1];
;     if (nloc == 0u) { xcd_barrier_complete(bar, b.x, nloc, nx); b.st[0] = nloc; b.st[1] = nx; }
; __global__ void __launch_bounds__(256, 2) fwd_megakernel(Params p) {
;     ...
;   xcd_barrier(gbar);
.Lmy_hg_done2_L0:
.LBB0_755:
	s_or_b64 exec, exec, s[10:11]
	s_waitcnt vmcnt(0)
	v_readlane_b32 s0, v255, 5
	v_readlane_b32 s1, v255, 6
	s_barrier
	s_and_saveexec_b64 s[8:9], s[0:1]
	s_cbranch_execz .LBB0_807
	v_mov_b32_e32 v0, 0x10800
	s_waitcnt vmcnt(0) expcnt(0) lgkmcnt(0)
	ds_read_b32 v2, v0
	v_mov_b32_e32 v0, 0x10804
	ds_read_b32 v0, v0
	s_waitcnt lgkmcnt(1)
	v_cmp_ne_u32_e32 vcc, 0, v2
	s_cbranch_vccnz .LBB0_771
	s_add_u32 s10, s22, 0x1c100200
	s_addc_u32 s11, s23, 0
	s_add_u32 s12, s22, 0x1c100400
	s_addc_u32 s13, s23, 0
	s_add_u32 s14, s22, 0x1c100500
	s_addc_u32 s15, s23, 0
	s_add_u32 s16, s22, 0x1c100600
	s_addc_u32 s17, s23, 0
	s_add_u32 s18, s22, 0x1c100700
	s_addc_u32 s19, s23, 0
	s_add_u32 s28, s22, 0x1c100800
	s_addc_u32 s29, s23, 0
	s_add_u32 s38, s22, 0x1c100900
	s_addc_u32 s39, s23, 0
	s_add_u32 s40, s22, 0x1c100a00
	s_addc_u32 s41, s23, 0
	s_add_u32 s42, s22, 0x1c100b00
	s_addc_u32 s43, s23, 0
	s_add_u32 s44, s22, 0x1c100c00
	s_addc_u32 s45, s23, 0
	s_add_u32 s46, s22, 0x1c100d00
	s_addc_u32 s47, s23, 0
	s_add_u32 s48, s22, 0x1c100e00
	s_addc_u32 s49, s23, 0
	s_add_u32 s50, s22, 0x1c100f00
	s_addc_u32 s51, s23, 0
	s_add_u32 s52, s22, 0x1c101000
	s_addc_u32 s53, s23, 0
	s_add_u32 s54, s22, 0x1c101100
	s_addc_u32 s55, s23, 0
	s_add_u32 s56, s22, 0x1c101200
	v_readlane_b32 s0, v255, 2
	s_addc_u32 s57, s23, 0
	s_mul_i32 s4, s27, s0
	s_add_u32 s58, s22, 0x1c101300
	s_mul_i32 s4, s4, s26
	s_addc_u32 s59, s23, 0
	s_mov_b32 s5, 1
	v_mov_b32_e32 v16, 0
	s_branch .LBB0_759

; #define RUN(k, ...) if (PH & (1 << k)) { __VA_ARGS__; if (REPM & (1 << k)) { xcd_barrier(gbar); __VA_ARGS__; } }
; DI bf16 f2bf(float a) { return (bf16)(pack2(a, 0.f) & 0xffffu); }
; DI int opaque_tid() { int t = threadIdx.x; asm volatile("" : "+v"(t)); return t; }
; DI void peer_hg_phase(const Params& p) {
;   unsigned char* ws = p.ws;
;   const int* ex = (const int*)(ws + OFF_EX);
;   const float* gt = (const float*)(ws + OFF_GT);
;   const float* sd = (const float*)(ws + OFF_SD);
;   const float* pa = (const float*)(ws + OFF_YB);
;   u32* hgp = (u32*)(ws + OFF_HGP);
;   const int tid = opaque_tid();
;   for (size_t i = (size_t)blockIdx.x * 256 + tid; i < (size_t)T_TOK * 128; i += (size_t)gridDim.x * 256) {
;     float a = 0.f;
; #pragma unroll
;     for (int s2 = 0; s2 < 8; ++s2) a += pa[(size_t)s2 * T_TOK * 128 + i];
;     a *= sd[i];
;     const float hgv = 0.5f * a * (1.f + erff(a * 0.70710678118654752f)) * gt[i];
;     hgp[i] = ((u32)ex[i] << 16) | (u32)f2bf(hgv);
;   }
; __global__ void __launch_bounds__(256, 2) fwd_megakernel(Params p) {
;     ...
;   RUN(15, peer_down2_phase(p, smem, 1, x1b, ctrs + 64))
;   xcd_barrier(gbar);
;   peer_hg_phase(p);
.LBB0_1571:
	s_or_b64 exec, exec, s[6:7]
	v_mov_b32_e32 v2, v160
	v_readlane_b32 s0, v255, 7
	s_waitcnt lgkmcnt(0)
	s_barrier
	s_mov_b64 s[6:7], exec
	v_add_u32_e32 v32, s0, v160
	s_lshl_b32 s64, s26, 8
	s_add_u32 s68, s22, 0x10000000
	s_addc_u32 s69, s23, 0
	s_add_u32 s70, s68, 0x800000
	s_addc_u32 s71, s69, 0
	s_add_u32 s72, s70, 0x800000
	s_addc_u32 s73, s71, 0
	s_add_u32 s74, s72, 0x800000
	s_addc_u32 s75, s73, 0
	s_add_u32 s76, s74, 0x800000
	s_addc_u32 s77, s75, 0
	s_add_u32 s78, s76, 0x800000
	s_addc_u32 s79, s77, 0
	s_add_u32 s80, s78, 0x800000
	s_addc_u32 s81, s79, 0
	s_add_u32 s82, s80, 0x800000
	s_addc_u32 s83, s81, 0
	s_add_u32 s84, s22, 0x1c400000
	s_addc_u32 s85, s23, 0
	s_add_u32 s86, s22, 0x18000000
	s_addc_u32 s87, s23, 0
	s_add_u32 s88, s22, 0x17800000
	s_addc_u32 s89, s23, 0
	s_add_u32 s90, s22, 0x1b800000
	s_addc_u32 s91, s23, 0
	s_mov_b32 s92, 0x378e98ab
	s_mov_b32 s93, 0x3b7cd369
	s_mov_b32 s94, 0xbcc618b2
	s_mov_b32 s95, 0x3dda74e4
	s_mov_b32 s96, 0x3f228afd
	s_mov_b32 s97, 0x3e03c728
	s_mov_b32 s98, 0xbfb8aa3b
	s_mov_b32 s99, 0x42ce8ed0
	s_mov_b32 s100, 0xc2b17218
	s_mov_b32 s101, 0x7fffffff
	v_mov_b32_e32 v84, 0x3ba10414
	v_mov_b32_e32 v85, 0xb9c68948
	v_mov_b32_e32 v86, 0x7f800000
	s_mov_b32 s65, 0x80000
	s_cmp_lg_u32 s26, 0x200
	s_cbranch_scc1 .Lmy_hg_loop_L1
	v_lshlrev_b32_e32 v33, 4, v32
	s_lshl_b32 s66, s64, 4
	v_add_u32_e32 v35, s66, v33
	global_load_dwordx4 v[36:39], v33, s[68:69]
	global_load_dwordx4 v[40:43], v33, s[70:71]
	global_load_dwordx4 v[44:47], v33, s[72:73]
	global_load_dwordx4 v[48:51], v33, s[74:75]
	global_load_dwordx4 v[52:55], v33, s[76:77]
	global_load_dwordx4 v[56:59], v33, s[78:79]
	global_load_dwordx4 v[60:63], v33, s[80:81]
	global_load_dwordx4 v[64:67], v33, s[82:83]
	global_load_dwordx4 v[68:71], v33, s[84:85]
	global_load_dwordx4 v[72:75], v33, s[86:87]
	global_load_dwordx4 v[76:79], v33, s[88:89]
	global_load_dwordx4 v[164:167], v35, s[68:69]
	global_load_dwordx4 v[168:171], v35, s[70:71]
	global_load_dwordx4 v[172:175], v35, s[72:73]
	global_load_dwordx4 v[176:179], v35, s[74:75]
	global_load_dwordx4 v[180:183], v35, s[76:77]
	global_load_dwordx4 v[184:187], v35, s[78:79]
	global_load_dwordx4 v[188:191], v35, s[80:81]
	global_load_dwordx4 v[192:195], v35, s[82:83]
	global_load_dwordx4 v[196:199], v35, s[84:85]
	global_load_dwordx4 v[200:203], v35, s[86:87]
	global_load_dwordx4 v[204:207], v35, s[88:89]
	s_waitcnt vmcnt(21)
	v_add_f32_e32 v36, 0, v36
	v_add_f32_e32 v37, 0, v37
	v_add_f32_e32 v38, 0, v38
	v_add_f32_e32 v39, 0, v39
	s_waitcnt vmcnt(20)
	v_add_f32_e32 v36, v36, v40
	v_add_f32_e32 v37, v37, v41
	v_add_f32_e32 v38, v38, v42
	v_add_f32_e32 v39, v39, v43
	s_waitcnt vmcnt(19)
	v_add_f32_e32 v36, v36, v44
	v_add_f32_e32 v37, v37, v45
	v_add_f32_e32 v38, v38, v46
	v_add_f32_e32 v39, v39, v47
	s_waitcnt vmcnt(18)
	v_add_f32_e32 v36, v36, v48
	v_add_f32_e32 v37, v37, v49
	v_add_f32_e32 v38, v38, v50
	v_add_f32_e32 v39, v39, v51
	s_waitcnt vmcnt(17)
	v_add_f32_e32 v36, v36, v52
	v_add_f32_e32 v37, v37, v53
	v_add_f32_e32 v38, v38, v54
	v_add_f32_e32 v39, v39, v55
	s_waitcnt vmcnt(16)
	v_add_f32_e32 v36, v36, v56
	v_add_f32_e32 v37, v37, v57
	v_add_f32_e32 v38, v38, v58
	v_add_f32_e32 v39, v39, v59
	s_waitcnt vmcnt(15)
	v_add_f32_e32 v36, v36, v60
	v_add_f32_e32 v37, v37, v61
	v_add_f32_e32 v38, v38, v62
	v_add_f32_e32 v39, v39, v63
	s_waitcnt vmcnt(14)
	v_add_f32_e32 v36, v36, v64
	v_add_f32_e32 v37, v37, v65
	v_add_f32_e32 v38, v38, v66
	v_add_f32_e32 v39, v39, v67
	s_waitcnt vmcnt(13)
	v_mul_f32_e32 v36, v36, v68
	v_mul_f32_e32 v37, v37, v69
	v_mul_f32_e32 v38, v38, v70
	v_mul_f32_e32 v39, v39, v71
	v_mul_f32_e32 v40, 0x3f3504f3, v36
	v_cmp_nlt_f32_e64 s[42:43], |v40|, 1.0
	s_and_saveexec_b64 s[44:45], s[42:43]
	s_xor_b64 s[42:43], exec, s[44:45]
	s_cbranch_execz .Lmy_hg_b_L1_0_u0
	v_fma_f32 v41, |v40|, s92, v85
	v_fma_f32 v41, |v40|, v41, s93
	v_fma_f32 v41, |v40|, v41, s94
	v_fma_f32 v41, |v40|, v41, s95
	v_fma_f32 v41, |v40|, v41, s96
	v_fma_f32 v41, |v40|, v41, s97
	v_fma_f32 v41, |v40|, v41, |v40|
	v_mul_f32_e32 v42, 0xbfb8aa3b, v41
	v_fma_f32 v43, v41, s98, -v42
	v_rndne_f32_e32 v44, v42
	v_fmac_f32_e32 v43, 0xb2a5705f, v41
	v_sub_f32_e32 v42, v42, v44
	v_add_f32_e32 v42, v42, v43
	v_cvt_i32_f32_e32 v43, v44
	v_exp_f32_e32 v42, v42
	v_cmp_nlt_f32_e32 vcc, s99, v41
	v_ldexp_f32 v42, v42, v43
	s_nop 0
	v_cndmask_b32_e32 v42, 0, v42, vcc
	v_cmp_ngt_f32_e32 vcc, s100, v41
	s_nop 1
	v_cndmask_b32_e32 v41, v86, v42, vcc
	v_sub_f32_e32 v41, 1.0, v41

; DI unsigned xb_ld(unsigned* p)              { return __hip_atomic_load(p, __ATOMIC_RELAXED, __HIP_MEMORY_SCOPE_AGENT); }
; DI void xcd_barrier_complete(unsigned* bar, unsigned x, unsigned& nloc, unsigned& nx) {
;   const unsigned G = gridDim.x * gridDim.y * gridDim.z;
;   unsigned sum, cnt, mine, sp = 0u;
;   for (;;) {
;     sum = 0u; cnt = 0u; mine = 0u;
; #pragma unroll
;     for (unsigned j = 0; j < 16; ++j) { const unsigned c = xb_ld(&bar[XB_XCNT(j)]); sum += c; cnt += (c > 0u) ? 1u : 0u; mine = (j == x) ? c : mine; }
; DI void xcd_barrier(const XcdBarrier& b) {
;   asm volatile("s_waitcnt vmcnt(0)" ::: "memory");
;   __syncthreads();
;   if (threadIdx.x == 0) {
;     unsigned* bar = b.bar;
;     __builtin_amdgcn_s_waitcnt(0);
;     unsigned nloc = b.st[0], nx = b.st[1];
;     if (nloc == 0u) { xcd_barrier_complete(bar, b.x, nloc, nx); b.st[0] = nloc; b.st[1] = nx; }
; __global__ void __launch_bounds__(256, 2) fwd_megakernel(Params p) {
;     ...
;   xcd_barrier(gbar);
.Lmy_hg_done2_L1:
.LBB0_1578:
	s_or_b64 exec, exec, s[6:7]
	s_waitcnt vmcnt(0)
	s_barrier
	s_mov_b64 s[2:3], exec
	v_readlane_b32 s0, v255, 5
	v_readlane_b32 s1, v255, 6
	s_and_b64 s[0:1], s[2:3], s[0:1]
	s_mov_b64 exec, s[0:1]
	s_cbranch_execz .LBB0_1630
	v_mov_b32_e32 v0, 0x10800
	s_waitcnt vmcnt(0) expcnt(0) lgkmcnt(0)
	ds_read_b32 v2, v0
	v_mov_b32_e32 v0, 0x10804
	ds_read_b32 v0, v0
	s_waitcnt lgkmcnt(1)
	v_cmp_ne_u32_e32 vcc, 0, v2
	s_cbranch_vccnz .LBB0_1594
	s_add_u32 s6, s22, 0x1c100200
	s_addc_u32 s7, s23, 0
	s_add_u32 s8, s22, 0x1c100400
	s_addc_u32 s9, s23, 0
	s_add_u32 s10, s22, 0x1c100500
	s_addc_u32 s11, s23, 0
	s_add_u32 s12, s22, 0x1c100600
	s_addc_u32 s13, s23, 0
	s_add_u32 s14, s22, 0x1c100700
	s_addc_u32 s15, s23, 0
	s_add_u32 s16, s22, 0x1c100800
	s_addc_u32 s17, s23, 0
	s_add_u32 s18, s22, 0x1c100900
	s_addc_u32 s19, s23, 0
	s_add_u32 s20, s22, 0x1c100a00
	s_addc_u32 s21, s23, 0
	s_add_u32 s28, s22, 0x1c100b00
	s_addc_u32 s29, s23, 0
	s_add_u32 s36, s22, 0x1c100c00
	s_addc_u32 s37, s23, 0
	s_add_u32 s38, s22, 0x1c100d00
	s_addc_u32 s39, s23, 0
	s_add_u32 s40, s22, 0x1c100e00
	s_addc_u32 s41, s23, 0
	s_add_u32 s42, s22, 0x1c100f00
	s_addc_u32 s43, s23, 0
	s_add_u32 s44, s22, 0x1c101000
	s_addc_u32 s45, s23, 0
	s_add_u32 s46, s22, 0x1c101100
	s_addc_u32 s47, s23, 0
	s_add_u32 s48, s22, 0x1c101200
	v_readlane_b32 s0, v255, 2
	s_addc_u32 s49, s23, 0
	s_mul_i32 s0, s27, s0
	s_add_u32 s50, s22, 0x1c101300
	s_mul_i32 s0, s0, s26
	s_addc_u32 s51, s23, 0
	s_mov_b32 s1, 1
	v_mov_b32_e32 v16, 0
	s_branch .LBB0_1582
